# attention loop: the 8 packed v_pk_fma_f32 of the score scaling split into scalar v_fma_f32 pairs
# baseline (speedup 1.0000x reference)
.LBB0_863:
	v_cndmask_b32_e64 v214, v153, v214, s[40:41]
	v_mul_f32_e32 v138, 0xbdd53b94, v214
	v_mov_b32_e32 v139, v138
	v_fmamk_f32 v82, v82, 0x3dd53b94, v138
	v_fmamk_f32 v83, v83, 0x3dd53b94, v138
	v_fmamk_f32 v84, v84, 0x3dd53b94, v138
	v_fmamk_f32 v85, v85, 0x3dd53b94, v138
	v_fmamk_f32 v86, v86, 0x3dd53b94, v138
	v_fmamk_f32 v87, v87, 0x3dd53b94, v138
	v_fmamk_f32 v88, v88, 0x3dd53b94, v138
	v_fmamk_f32 v89, v89, 0x3dd53b94, v138
	v_fmamk_f32 v90, v90, 0x3dd53b94, v138
	v_fmamk_f32 v91, v91, 0x3dd53b94, v138
	v_fmamk_f32 v92, v92, 0x3dd53b94, v138
	v_fmamk_f32 v93, v93, 0x3dd53b94, v138
	v_fmamk_f32 v94, v94, 0x3dd53b94, v138
	v_fmamk_f32 v95, v95, 0x3dd53b94, v138
	v_fmamk_f32 v96, v96, 0x3dd53b94, v138
	v_fmac_f32_e32 v139, 0x3dd53b94, v97
	v_exp_f32_e32 v153, v82
	v_exp_f32_e32 v154, v83
	v_exp_f32_e32 v230, v84
	v_exp_f32_e32 v231, v85
	v_exp_f32_e32 v232, v86
	v_exp_f32_e32 v233, v87
	v_exp_f32_e32 v155, v88
	v_exp_f32_e32 v229, v89
	v_exp_f32_e32 v151, v90
	v_exp_f32_e32 v156, v91
	v_exp_f32_e32 v157, v92
	v_exp_f32_e32 v158, v93
	v_exp_f32_e32 v148, v94
	v_exp_f32_e32 v149, v95
	v_exp_f32_e32 v150, v96
	v_exp_f32_e32 v159, v139
	v_fma_f32 v144, v66, s30, v138
	v_fma_f32 v145, v67, s30, v138
	v_add_f32_e32 v66, v227, v228
	v_fmac_f32_e32 v66, v213, v198
	v_add_f32_e32 v198, v235, v236
	s_addk_i32 s12, 0x80
	s_addk_i32 s13, 0x80
	v_fma_f32 v142, v68, s30, v138
	v_fma_f32 v143, v69, s30, v138
	v_fma_f32 v136, v70, s30, v138
	v_fma_f32 v137, v71, s30, v138
	v_fma_f32 v134, v72, s30, v138
	v_fma_f32 v135, v73, s30, v138
	v_fma_f32 v132, v74, s30, v138
	v_fma_f32 v133, v75, s30, v138
	v_fma_f32 v146, v76, s30, v138
	v_fma_f32 v147, v77, s30, v138
	v_fma_f32 v140, v78, s30, v138
	v_fma_f32 v141, v79, s30, v138
	v_fma_f32 v139, v81, s30, v138
	v_fma_f32 v138, v80, s30, v138
	v_fmac_f32_e32 v198, v66, v234
	s_cmp_ge_u32 s100, 0x2000
	s_cbranch_scc1 .Lmy_att_l2
	s_waitcnt vmcnt(0) lgkmcnt(0)
	s_barrier
